# row passes P4/P8/P10: for split-K tail rows, all 4-slab chunks are touched in the first chunk's block so the three later chunk loads per row hit cache instead of exposing a full latency each
# speedup vs baseline: 1.0011x; 1.0011x over previous
; __device__ __forceinline__ float bf2f(unsigned b) { return __uint_as_float(b << 16); }
; template <int RB, int XB>
; __device__ __forceinline__ void row_op2(const RowPtrs (&r)[NR], bool has_src, const float* gpost, const float* gnext, int lane) {
;     ...
; #pragma unroll
;     for (int k = 0; k < NR; ++k)
; #pragma unroll
;         for (int j = 0; j < 4; ++j) {
;             if (RB) { const u32x2 wv = ((const u32x2*)r[k].resid)[lane + 64 * j]; x[k][j] = (f32x4){bf2f(wv.x & 0xffffu), bf2f(wv.x >> 16), bf2f(wv.y & 0xffffu), bf2f(wv.y >> 16)}; }
;             else x[k][j] = ((const f32x4*)r[k].resid)[lane + 64 * j]; }
;     if (has_src) {
;         u32x2 sb[NR][4];
; #pragma unroll
;         for (int k = 0; k < NR; ++k)
; #pragma unroll
;             for (int j = 0; j < 4; ++j) {
;                 if (r[k].srcf != nullptr) { const float* sf = r[k].srcf; s[k][j] = ((const f32x4*)sf)[lane + 64 * j];
;                     if (r[k].parts4) s[k][j] = (s[k][j] + ((const f32x4*)(sf + (size_t)TS * D))[lane + 64 * j]) + (((const f32x4*)(sf + (size_t)2 * TS * D))[lane + 64 * j] + ((const f32x4*)(sf + (size_t)3 * TS * D))[lane + 64 * j]); }
.LBB0_531:
	s_add_i32 s56, s0, 0xffffc000
	s_lshl_b64 s[6:7], s[56:57], 12
	s_add_u32 s68, s4, s6
	s_addc_u32 s69, s5, s7
	s_add_u32 s1, s18, s6
	s_addc_u32 s8, s19, s7
	s_cmpk_lt_i32 s0, 0x4000
	s_cselect_b32 s7, 0, s69
	s_cselect_b32 s6, 0, s68
	s_cselect_b32 s9, s33, s8
	s_cselect_b32 s8, s3, s1
	s_cmpk_gt_i32 s0, 0x3fff
	s_cselect_b64 s[86:87], -1, 0
	s_add_i32 s1, s96, s0
	s_cmpk_lt_i32 s1, 0x4200
	s_cselect_b32 s10, s1, s0
	s_add_i32 s56, s10, 0xffffc000
	s_ashr_i32 s11, s10, 31
	s_lshl_b64 s[70:71], s[56:57], 12
	s_lshl_b64 s[12:13], s[10:11], 12
	s_add_u32 s35, s16, s12
	s_addc_u32 s56, s17, s13
	s_add_u32 s67, s18, s70
	s_addc_u32 s72, s19, s71
	s_cmpk_lt_i32 s10, 0x4000
	s_cselect_b64 s[76:77], -1, 0
	s_and_b64 s[12:13], s[76:77], exec
	s_cselect_b32 s79, s56, s72
	s_cselect_b32 s78, s35, s67
	s_add_i32 s35, s96, s1
	s_cmpk_lt_i32 s35, 0x4200
	s_cselect_b32 s12, s35, s0
	s_add_i32 s56, s12, 0xffffc000
	s_ashr_i32 s13, s12, 31
	s_lshl_b64 s[72:73], s[56:57], 12
	s_lshl_b64 s[0:1], s[12:13], 12
	s_add_u32 s56, s16, s0
	s_addc_u32 s67, s17, s1
	s_add_u32 s80, s18, s72
	s_addc_u32 s81, s19, s73
	s_cmpk_lt_i32 s12, 0x4000
	s_cselect_b64 s[74:75], -1, 0
	s_and_b64 s[0:1], s[74:75], exec
	s_cselect_b32 s1, s67, s81
	s_cselect_b32 s0, s56, s80
	global_load_dwordx4 v[44:47], v133, s[8:9]
	global_load_dwordx4 v[40:43], v133, s[8:9] offset:1024
	global_load_dwordx4 v[36:39], v133, s[8:9] offset:2048
	global_load_dwordx4 v[32:35], v133, s[8:9] offset:3072
	global_load_dwordx4 v[28:31], v133, s[78:79]
	global_load_dwordx4 v[24:27], v133, s[78:79] offset:1024
	global_load_dwordx4 v[20:23], v133, s[78:79] offset:2048
	global_load_dwordx4 v[16:19], v133, s[78:79] offset:3072
	global_load_dwordx4 v[12:15], v133, s[0:1]
	global_load_dwordx4 v[8:11], v133, s[0:1] offset:1024
	global_load_dwordx4 v[4:7], v133, s[0:1] offset:2048
	global_load_dwordx4 v[0:3], v133, s[0:1] offset:3072
	s_cmp_eq_u64 s[6:7], 0
	s_cselect_b64 s[0:1], -1, 0
	s_cmp_lg_u64 s[6:7], 0
	s_cselect_b64 s[84:85], -1, 0
	s_add_u32 s80, s6, 0x200000
	s_addc_u32 s81, s7, 0
	s_add_u32 s78, s6, 0x400000
	s_addc_u32 s79, s7, 0
	s_add_u32 s82, s6, 0x600000
	v_cndmask_b32_e64 v48, 0, 1, s[86:87]
	s_addc_u32 s83, s7, 0
	s_mov_b64 s[8:9], -1
	s_and_b64 vcc, exec, s[0:1]
	v_cmp_ne_u32_e64 s[6:7], 1, v48
	s_cbranch_vccnz .LBB0_535
	global_load_dwordx4 v[48:51], v133, s[68:69]
	s_and_b64 vcc, exec, s[6:7]
	s_cbranch_vccnz .LBB0_534
	global_load_dwordx4 v[52:55], v133, s[80:81]
	global_load_dwordx4 v[56:59], v133, s[78:79]
	global_load_dwordx4 v[60:63], v133, s[82:83]
	global_load_dwordx4 v[200:203], v133, s[68:69] offset:1024
	global_load_dwordx4 v[200:203], v133, s[68:69] offset:2048
	global_load_dwordx4 v[200:203], v133, s[68:69] offset:3072
	global_load_dwordx4 v[200:203], v133, s[80:81] offset:1024
	global_load_dwordx4 v[200:203], v133, s[80:81] offset:2048
	global_load_dwordx4 v[200:203], v133, s[80:81] offset:3072
	global_load_dwordx4 v[200:203], v133, s[78:79] offset:1024
	global_load_dwordx4 v[200:203], v133, s[78:79] offset:2048
	global_load_dwordx4 v[200:203], v133, s[78:79] offset:3072
	global_load_dwordx4 v[200:203], v133, s[82:83] offset:1024
	global_load_dwordx4 v[200:203], v133, s[82:83] offset:2048
	global_load_dwordx4 v[200:203], v133, s[82:83] offset:3072
	s_waitcnt vmcnt(0)
	v_pk_add_f32 v[50:51], v[50:51], v[54:55]
	v_pk_add_f32 v[48:49], v[48:49], v[52:53]
	v_pk_add_f32 v[52:53], v[58:59], v[62:63]
	v_pk_add_f32 v[54:55], v[56:57], v[60:61]
	v_pk_add_f32 v[50:51], v[50:51], v[52:53]
	v_pk_add_f32 v[48:49], v[48:49], v[54:55]

; __device__ __forceinline__ float bf2f(unsigned b) { return __uint_as_float(b << 16); }
; template <int RB, int XB>
; __device__ __forceinline__ void row_op2(const RowPtrs (&r)[NR], bool has_src, const float* gpost, const float* gnext, int lane) {
;     ...
; #pragma unroll
;     for (int k = 0; k < NR; ++k)
; #pragma unroll
;         for (int j = 0; j < 4; ++j) {
;             if (RB) { const u32x2 wv = ((const u32x2*)r[k].resid)[lane + 64 * j]; x[k][j] = (f32x4){bf2f(wv.x & 0xffffu), bf2f(wv.x >> 16), bf2f(wv.y & 0xffffu), bf2f(wv.y >> 16)}; }
;             else x[k][j] = ((const f32x4*)r[k].resid)[lane + 64 * j]; }
;     if (has_src) {
;         u32x2 sb[NR][4];
; #pragma unroll
;         for (int k = 0; k < NR; ++k)
; #pragma unroll
;             for (int j = 0; j < 4; ++j) {
;                 if (r[k].srcf != nullptr) { const float* sf = r[k].srcf; s[k][j] = ((const f32x4*)sf)[lane + 64 * j];
;                     if (r[k].parts4) s[k][j] = (s[k][j] + ((const f32x4*)(sf + (size_t)TS * D))[lane + 64 * j]) + (((const f32x4*)(sf + (size_t)2 * TS * D))[lane + 64 * j] + ((const f32x4*)(sf + (size_t)3 * TS * D))[lane + 64 * j]); }
.LBB0_555:
	s_lshl_b64 s[68:69], s[10:11], 10
	s_add_u32 s78, s4, s70
	s_addc_u32 s79, s5, s71
	s_and_b64 s[6:7], s[76:77], exec
	s_cselect_b32 s9, 0, s79
	s_cselect_b32 s8, 0, s78
	s_lshl_b64 s[6:7], s[68:69], 1
	s_add_u32 s70, s28, s6
	s_addc_u32 s71, s29, s7
	s_cmpk_gt_i32 s10, 0x3fff
	s_cselect_b64 s[86:87], -1, 0
	s_cmp_eq_u64 s[8:9], 0
	s_cselect_b64 s[6:7], -1, 0
	s_cmp_lg_u64 s[8:9], 0
	s_cselect_b64 s[84:85], -1, 0
	s_add_u32 s80, s8, 0x200000
	s_addc_u32 s81, s9, 0
	s_add_u32 s76, s8, 0x400000
	s_addc_u32 s77, s9, 0
	s_add_u32 s82, s8, 0x600000
	v_cndmask_b32_e64 v64, 0, 1, s[86:87]
	s_addc_u32 s83, s9, 0
	s_mov_b64 s[10:11], -1
	s_and_b64 vcc, exec, s[6:7]
	v_cmp_ne_u32_e64 s[8:9], 1, v64
	s_cbranch_vccnz .LBB0_559
	global_load_dwordx4 v[64:67], v133, s[78:79]
	s_and_b64 vcc, exec, s[8:9]
	s_cbranch_vccnz .LBB0_558
	global_load_dwordx4 v[68:71], v133, s[80:81]
	global_load_dwordx4 v[72:75], v133, s[76:77]
	global_load_dwordx4 v[76:79], v133, s[82:83]
	global_load_dwordx4 v[200:203], v133, s[78:79] offset:1024
	global_load_dwordx4 v[200:203], v133, s[78:79] offset:2048
	global_load_dwordx4 v[200:203], v133, s[78:79] offset:3072
	global_load_dwordx4 v[200:203], v133, s[80:81] offset:1024
	global_load_dwordx4 v[200:203], v133, s[80:81] offset:2048
	global_load_dwordx4 v[200:203], v133, s[80:81] offset:3072
	global_load_dwordx4 v[200:203], v133, s[76:77] offset:1024
	global_load_dwordx4 v[200:203], v133, s[76:77] offset:2048
	global_load_dwordx4 v[200:203], v133, s[76:77] offset:3072
	global_load_dwordx4 v[200:203], v133, s[82:83] offset:1024
	global_load_dwordx4 v[200:203], v133, s[82:83] offset:2048
	global_load_dwordx4 v[200:203], v133, s[82:83] offset:3072
	s_waitcnt vmcnt(0)
	v_pk_add_f32 v[66:67], v[66:67], v[70:71]
	v_pk_add_f32 v[64:65], v[64:65], v[68:69]
	v_pk_add_f32 v[68:69], v[74:75], v[78:79]
	v_pk_add_f32 v[70:71], v[72:73], v[76:77]
	v_pk_add_f32 v[66:67], v[66:67], v[68:69]
	v_pk_add_f32 v[64:65], v[64:65], v[70:71]

; __device__ __forceinline__ float bf2f(unsigned b) { return __uint_as_float(b << 16); }
; template <int RB, int XB>
; __device__ __forceinline__ void row_op2(const RowPtrs (&r)[NR], bool has_src, const float* gpost, const float* gnext, int lane) {
;     ...
; #pragma unroll
;     for (int k = 0; k < NR; ++k)
; #pragma unroll
;         for (int j = 0; j < 4; ++j) {
;             if (RB) { const u32x2 wv = ((const u32x2*)r[k].resid)[lane + 64 * j]; x[k][j] = (f32x4){bf2f(wv.x & 0xffffu), bf2f(wv.x >> 16), bf2f(wv.y & 0xffffu), bf2f(wv.y >> 16)}; }
;             else x[k][j] = ((const f32x4*)r[k].resid)[lane + 64 * j]; }
;     if (has_src) {
;         u32x2 sb[NR][4];
; #pragma unroll
;         for (int k = 0; k < NR; ++k)
; #pragma unroll
;             for (int j = 0; j < 4; ++j) {
;                 if (r[k].srcf != nullptr) { const float* sf = r[k].srcf; s[k][j] = ((const f32x4*)sf)[lane + 64 * j];
;                     if (r[k].parts4) s[k][j] = (s[k][j] + ((const f32x4*)(sf + (size_t)TS * D))[lane + 64 * j]) + (((const f32x4*)(sf + (size_t)2 * TS * D))[lane + 64 * j] + ((const f32x4*)(sf + (size_t)3 * TS * D))[lane + 64 * j]); }
.LBB0_579:
	s_lshl_b64 s[70:71], s[12:13], 10
	s_add_u32 s76, s4, s72
	s_addc_u32 s77, s5, s73
	s_and_b64 s[8:9], s[74:75], exec
	s_cselect_b32 s11, 0, s77
	s_cselect_b32 s10, 0, s76
	s_lshl_b64 s[8:9], s[70:71], 1
	s_add_u32 s72, s28, s8
	s_addc_u32 s73, s29, s9
	s_cmpk_gt_i32 s12, 0x3fff
	s_cselect_b64 s[84:85], -1, 0
	s_cmp_eq_u64 s[10:11], 0
	s_cselect_b64 s[8:9], -1, 0
	s_cmp_lg_u64 s[10:11], 0
	s_cselect_b64 s[82:83], -1, 0
	s_add_u32 s78, s10, 0x200000
	s_addc_u32 s79, s11, 0
	s_add_u32 s74, s10, 0x400000
	s_addc_u32 s75, s11, 0
	s_add_u32 s80, s10, 0x600000
	v_cndmask_b32_e64 v80, 0, 1, s[84:85]
	s_addc_u32 s81, s11, 0
	s_mov_b64 s[12:13], -1
	s_and_b64 vcc, exec, s[8:9]
	v_cmp_ne_u32_e64 s[10:11], 1, v80
	s_cbranch_vccnz .LBB0_583
	global_load_dwordx4 v[80:83], v133, s[76:77]
	s_and_b64 vcc, exec, s[10:11]
	s_cbranch_vccnz .LBB0_582
	global_load_dwordx4 v[84:87], v133, s[78:79]
	global_load_dwordx4 v[88:91], v133, s[74:75]
	global_load_dwordx4 v[92:95], v133, s[80:81]
	global_load_dwordx4 v[200:203], v133, s[76:77] offset:1024
	global_load_dwordx4 v[200:203], v133, s[76:77] offset:2048
	global_load_dwordx4 v[200:203], v133, s[76:77] offset:3072
	global_load_dwordx4 v[200:203], v133, s[78:79] offset:1024
	global_load_dwordx4 v[200:203], v133, s[78:79] offset:2048
	global_load_dwordx4 v[200:203], v133, s[78:79] offset:3072
	global_load_dwordx4 v[200:203], v133, s[74:75] offset:1024
	global_load_dwordx4 v[200:203], v133, s[74:75] offset:2048
	global_load_dwordx4 v[200:203], v133, s[74:75] offset:3072
	global_load_dwordx4 v[200:203], v133, s[80:81] offset:1024
	global_load_dwordx4 v[200:203], v133, s[80:81] offset:2048
	global_load_dwordx4 v[200:203], v133, s[80:81] offset:3072
	s_waitcnt vmcnt(0)
	v_pk_add_f32 v[82:83], v[82:83], v[86:87]
	v_pk_add_f32 v[80:81], v[80:81], v[84:85]
	v_pk_add_f32 v[84:85], v[90:91], v[94:95]
	v_pk_add_f32 v[86:87], v[88:89], v[92:93]
	v_pk_add_f32 v[82:83], v[82:83], v[84:85]
	v_pk_add_f32 v[80:81], v[80:81], v[86:87]

; __device__ __forceinline__ float bf2f(unsigned b) { return __uint_as_float(b << 16); }
; template <int RB, int XB>
; __device__ __forceinline__ void row_op2(const RowPtrs (&r)[NR], bool has_src, const float* gpost, const float* gnext, int lane) {
;     ...
;             if (RB) { const u32x2 wv = ((const u32x2*)r[k].resid)[lane + 64 * j]; x[k][j] = (f32x4){bf2f(wv.x & 0xffffu), bf2f(wv.x >> 16), bf2f(wv.y & 0xffffu), bf2f(wv.y >> 16)}; }
;             else x[k][j] = ((const f32x4*)r[k].resid)[lane + 64 * j]; }
;     if (has_src) {
;         u32x2 sb[NR][4];
; #pragma unroll
;         for (int k = 0; k < NR; ++k)
; #pragma unroll
;             for (int j = 0; j < 4; ++j) {
;                 if (r[k].srcf != nullptr) { const float* sf = r[k].srcf; s[k][j] = ((const f32x4*)sf)[lane + 64 * j];
;                     if (r[k].parts4) s[k][j] = (s[k][j] + ((const f32x4*)(sf + (size_t)TS * D))[lane + 64 * j]) + (((const f32x4*)(sf + (size_t)2 * TS * D))[lane + 64 * j] + ((const f32x4*)(sf + (size_t)3 * TS * D))[lane + 64 * j]); }
.LBB0_987:
	s_add_i32 s24, s0, 0xffffc000
	s_lshl_b64 s[6:7], s[24:25], 12
	s_add_u32 s10, s92, s6
	s_addc_u32 s11, s93, s7
	s_cmpk_gt_i32 s0, 0x3fff
	s_cselect_b64 s[6:7], -1, 0
	v_cndmask_b32_e64 v2, 0, 1, s[6:7]
	s_and_b64 s[6:7], s[6:7], exec
	s_cselect_b32 s7, s11, 0
	s_cselect_b32 s6, s10, 0
	s_add_i32 s1, s96, s0
	s_cmpk_lt_i32 s1, 0x4200
	s_cselect_b32 s44, s1, s0
	s_ashr_i32 s45, s44, 31
	s_add_i32 s43, s96, s1
	s_cmpk_lt_i32 s43, 0x4200
	s_cselect_b32 s46, s43, s0
	s_ashr_i32 s47, s46, 31
	v_lshl_add_u64 v[0:1], s[40:41], 0, v[134:135]
	s_lshl_b64 s[0:1], s[44:45], 11
	global_load_dwordx2 v[86:87], v[0:1], off
	global_load_dwordx2 v[84:85], v[0:1], off offset:512
	global_load_dwordx2 v[82:83], v[0:1], off offset:1024
	global_load_dwordx2 v[80:81], v[0:1], off offset:1536
	v_lshl_add_u64 v[0:1], v[56:57], 0, s[0:1]
	s_lshl_b64 s[0:1], s[46:47], 11
	global_load_dwordx2 v[78:79], v[0:1], off
	global_load_dwordx2 v[76:77], v[0:1], off offset:512
	global_load_dwordx2 v[74:75], v[0:1], off offset:1024
	global_load_dwordx2 v[72:73], v[0:1], off offset:1536
	v_lshl_add_u64 v[0:1], v[56:57], 0, s[0:1]
	global_load_dwordx2 v[70:71], v[0:1], off
	global_load_dwordx2 v[68:69], v[0:1], off offset:512
	global_load_dwordx2 v[66:67], v[0:1], off offset:1024
	global_load_dwordx2 v[64:65], v[0:1], off offset:1536
	s_cmp_eq_u64 s[6:7], 0
	s_cselect_b64 s[0:1], -1, 0
	s_cmp_lg_u64 s[6:7], 0
	s_cselect_b64 s[54:55], -1, 0
	s_add_u32 s50, s6, 0x200000
	s_addc_u32 s51, s7, 0
	s_add_u32 s12, s6, 0x400000
	s_addc_u32 s13, s7, 0
	s_add_u32 s48, s6, 0x600000
	s_addc_u32 s49, s7, 0
	s_mov_b64 s[8:9], -1
	s_and_b64 vcc, exec, s[0:1]
	v_lshlrev_b32_e32 v44, 4, v128
	v_cmp_ne_u32_e64 s[6:7], 1, v2
	s_cbranch_vccnz .LBB0_991
	global_load_dwordx4 v[0:3], v44, s[10:11]
	s_and_b64 vcc, exec, s[6:7]
	s_cbranch_vccnz .LBB0_990
	global_load_dwordx4 v[4:7], v44, s[50:51]
	global_load_dwordx4 v[8:11], v44, s[12:13]
	global_load_dwordx4 v[12:15], v44, s[48:49]
	global_load_dwordx4 v[200:203], v44, s[10:11] offset:1024
	global_load_dwordx4 v[200:203], v44, s[10:11] offset:2048
	global_load_dwordx4 v[200:203], v44, s[10:11] offset:3072
	global_load_dwordx4 v[200:203], v44, s[50:51] offset:1024
	global_load_dwordx4 v[200:203], v44, s[50:51] offset:2048
	global_load_dwordx4 v[200:203], v44, s[50:51] offset:3072
	global_load_dwordx4 v[200:203], v44, s[12:13] offset:1024
	global_load_dwordx4 v[200:203], v44, s[12:13] offset:2048
	global_load_dwordx4 v[200:203], v44, s[12:13] offset:3072
	global_load_dwordx4 v[200:203], v44, s[48:49] offset:1024
	global_load_dwordx4 v[200:203], v44, s[48:49] offset:2048
	global_load_dwordx4 v[200:203], v44, s[48:49] offset:3072
	s_waitcnt vmcnt(0)
	v_pk_add_f32 v[2:3], v[2:3], v[6:7]
	v_pk_add_f32 v[0:1], v[0:1], v[4:5]
	v_pk_add_f32 v[4:5], v[10:11], v[14:15]
	v_pk_add_f32 v[6:7], v[8:9], v[12:13]
	v_pk_add_f32 v[2:3], v[2:3], v[4:5]
	v_pk_add_f32 v[0:1], v[0:1], v[6:7]

; __device__ __forceinline__ float bf2f(unsigned b) { return __uint_as_float(b << 16); }
; template <int RB, int XB>
; __device__ __forceinline__ void row_op2(const RowPtrs (&r)[NR], bool has_src, const float* gpost, const float* gnext, int lane) {
;     ...
; #pragma unroll
;     for (int k = 0; k < NR; ++k)
; #pragma unroll
;         for (int j = 0; j < 4; ++j) {
;             if (RB) { const u32x2 wv = ((const u32x2*)r[k].resid)[lane + 64 * j]; x[k][j] = (f32x4){bf2f(wv.x & 0xffffu), bf2f(wv.x >> 16), bf2f(wv.y & 0xffffu), bf2f(wv.y >> 16)}; }
;             else x[k][j] = ((const f32x4*)r[k].resid)[lane + 64 * j]; }
;     if (has_src) {
;         u32x2 sb[NR][4];
; #pragma unroll
;         for (int k = 0; k < NR; ++k)
; #pragma unroll
;             for (int j = 0; j < 4; ++j) {
;                 if (r[k].srcf != nullptr) { const float* sf = r[k].srcf; s[k][j] = ((const f32x4*)sf)[lane + 64 * j];
;                     if (r[k].parts4) s[k][j] = (s[k][j] + ((const f32x4*)(sf + (size_t)TS * D))[lane + 64 * j]) + (((const f32x4*)(sf + (size_t)2 * TS * D))[lane + 64 * j] + ((const f32x4*)(sf + (size_t)3 * TS * D))[lane + 64 * j]); }
.LBB0_1011:
	s_add_i32 s24, s44, 0xffffc000
	s_lshl_b64 s[6:7], s[44:45], 10
	s_lshl_b64 s[8:9], s[24:25], 12
	s_add_u32 s12, s92, s8
	s_addc_u32 s13, s93, s9
	s_cmpk_gt_i32 s44, 0x3fff
	s_cselect_b64 s[8:9], -1, 0
	v_cndmask_b32_e64 v16, 0, 1, s[8:9]
	s_and_b64 s[8:9], s[8:9], exec
	s_cselect_b32 s9, s13, 0
	s_cselect_b32 s8, s12, 0
	s_lshl_b64 s[6:7], s[6:7], 1
	s_add_u32 s48, s52, s6
	s_addc_u32 s49, s53, s7
	s_cmp_eq_u64 s[8:9], 0
	s_cselect_b64 s[6:7], -1, 0
	s_cmp_lg_u64 s[8:9], 0
	s_cselect_b64 s[58:59], -1, 0
	s_add_u32 s56, s8, 0x200000
	s_addc_u32 s57, s9, 0
	s_add_u32 s50, s8, 0x400000
	s_addc_u32 s51, s9, 0
	s_add_u32 s54, s8, 0x600000
	s_addc_u32 s55, s9, 0
	s_mov_b64 s[10:11], -1
	s_and_b64 vcc, exec, s[6:7]
	v_cmp_ne_u32_e64 s[8:9], 1, v16
	s_cbranch_vccnz .LBB0_1015
	global_load_dwordx4 v[16:19], v44, s[12:13]
	s_and_b64 vcc, exec, s[8:9]
	s_cbranch_vccnz .LBB0_1014
	global_load_dwordx4 v[20:23], v44, s[56:57]
	global_load_dwordx4 v[24:27], v44, s[50:51]
	global_load_dwordx4 v[28:31], v44, s[54:55]
	global_load_dwordx4 v[200:203], v44, s[12:13] offset:1024
	global_load_dwordx4 v[200:203], v44, s[12:13] offset:2048
	global_load_dwordx4 v[200:203], v44, s[12:13] offset:3072
	global_load_dwordx4 v[200:203], v44, s[56:57] offset:1024
	global_load_dwordx4 v[200:203], v44, s[56:57] offset:2048
	global_load_dwordx4 v[200:203], v44, s[56:57] offset:3072
	global_load_dwordx4 v[200:203], v44, s[50:51] offset:1024
	global_load_dwordx4 v[200:203], v44, s[50:51] offset:2048
	global_load_dwordx4 v[200:203], v44, s[50:51] offset:3072
	global_load_dwordx4 v[200:203], v44, s[54:55] offset:1024
	global_load_dwordx4 v[200:203], v44, s[54:55] offset:2048
	global_load_dwordx4 v[200:203], v44, s[54:55] offset:3072
	s_waitcnt vmcnt(0)
	v_pk_add_f32 v[18:19], v[18:19], v[22:23]
	v_pk_add_f32 v[16:17], v[16:17], v[20:21]
	v_pk_add_f32 v[20:21], v[26:27], v[30:31]
	v_pk_add_f32 v[22:23], v[24:25], v[28:29]
	v_pk_add_f32 v[18:19], v[18:19], v[20:21]
	v_pk_add_f32 v[16:17], v[16:17], v[22:23]

; __device__ __forceinline__ float bf2f(unsigned b) { return __uint_as_float(b << 16); }
; template <int RB, int XB>
; __device__ __forceinline__ void row_op2(const RowPtrs (&r)[NR], bool has_src, const float* gpost, const float* gnext, int lane) {
;     ...
; #pragma unroll
;     for (int k = 0; k < NR; ++k)
; #pragma unroll
;         for (int j = 0; j < 4; ++j) {
;             if (RB) { const u32x2 wv = ((const u32x2*)r[k].resid)[lane + 64 * j]; x[k][j] = (f32x4){bf2f(wv.x & 0xffffu), bf2f(wv.x >> 16), bf2f(wv.y & 0xffffu), bf2f(wv.y >> 16)}; }
;             else x[k][j] = ((const f32x4*)r[k].resid)[lane + 64 * j]; }
;     if (has_src) {
;         u32x2 sb[NR][4];
; #pragma unroll
;         for (int k = 0; k < NR; ++k)
; #pragma unroll
;             for (int j = 0; j < 4; ++j) {
;                 if (r[k].srcf != nullptr) { const float* sf = r[k].srcf; s[k][j] = ((const f32x4*)sf)[lane + 64 * j];
;                     if (r[k].parts4) s[k][j] = (s[k][j] + ((const f32x4*)(sf + (size_t)TS * D))[lane + 64 * j]) + (((const f32x4*)(sf + (size_t)2 * TS * D))[lane + 64 * j] + ((const f32x4*)(sf + (size_t)3 * TS * D))[lane + 64 * j]); }
.LBB0_1035:
	s_add_i32 s24, s46, 0xffffc000
	s_lshl_b64 s[8:9], s[46:47], 10
	s_lshl_b64 s[10:11], s[24:25], 12
	s_add_u32 s54, s92, s10
	s_addc_u32 s55, s93, s11
	s_cmpk_gt_i32 s46, 0x3fff
	s_cselect_b64 s[10:11], -1, 0
	v_cndmask_b32_e64 v32, 0, 1, s[10:11]
	s_and_b64 s[10:11], s[10:11], exec
	s_cselect_b32 s11, s55, 0
	s_cselect_b32 s10, s54, 0
	s_lshl_b64 s[8:9], s[8:9], 1
	s_add_u32 s50, s52, s8
	s_addc_u32 s51, s53, s9
	s_cmp_eq_u64 s[10:11], 0
	s_cselect_b64 s[8:9], -1, 0
	s_cmp_lg_u64 s[10:11], 0
	s_cselect_b64 s[62:63], -1, 0
	s_add_u32 s60, s10, 0x200000
	s_addc_u32 s61, s11, 0
	s_add_u32 s56, s10, 0x400000
	s_addc_u32 s57, s11, 0
	s_add_u32 s58, s10, 0x600000
	s_addc_u32 s59, s11, 0
	s_mov_b64 s[12:13], -1
	s_and_b64 vcc, exec, s[8:9]
	v_cmp_ne_u32_e64 s[10:11], 1, v32
	s_cbranch_vccnz .LBB0_1039
	global_load_dwordx4 v[32:35], v44, s[54:55]
	s_and_b64 vcc, exec, s[10:11]
	s_cbranch_vccnz .LBB0_1038
	global_load_dwordx4 v[36:39], v44, s[60:61]
	global_load_dwordx4 v[40:43], v44, s[56:57]
	global_load_dwordx4 v[104:107], v44, s[58:59]
	global_load_dwordx4 v[200:203], v44, s[54:55] offset:1024
	global_load_dwordx4 v[200:203], v44, s[54:55] offset:2048
	global_load_dwordx4 v[200:203], v44, s[54:55] offset:3072
	global_load_dwordx4 v[200:203], v44, s[60:61] offset:1024
	global_load_dwordx4 v[200:203], v44, s[60:61] offset:2048
	global_load_dwordx4 v[200:203], v44, s[60:61] offset:3072
	global_load_dwordx4 v[200:203], v44, s[56:57] offset:1024
	global_load_dwordx4 v[200:203], v44, s[56:57] offset:2048
	global_load_dwordx4 v[200:203], v44, s[56:57] offset:3072
	global_load_dwordx4 v[200:203], v44, s[58:59] offset:1024
	global_load_dwordx4 v[200:203], v44, s[58:59] offset:2048
	global_load_dwordx4 v[200:203], v44, s[58:59] offset:3072
	s_waitcnt vmcnt(0)
	v_pk_add_f32 v[34:35], v[34:35], v[38:39]
	v_pk_add_f32 v[32:33], v[32:33], v[36:37]
	v_pk_add_f32 v[36:37], v[42:43], v[106:107]
	v_pk_add_f32 v[38:39], v[40:41], v[104:105]
	v_pk_add_f32 v[34:35], v[34:35], v[36:37]
	v_pk_add_f32 v[32:33], v[32:33], v[38:39]

; __device__ __forceinline__ void row_final2(const FinPtrs (&r)[NR], const float* g, int lane) {
;     ...
;             else { const float* gls = r[k].gls;
;                 gl = (((const f32x4*)gls)[lane + 64 * j] + ((const f32x4*)(gls + (size_t)TS * D))[lane + 64 * j]) + (((const f32x4*)(gls + (size_t)2 * TS * D))[lane + 64 * j] + ((const f32x4*)(gls + (size_t)3 * TS * D))[lane + 64 * j]); }
.LBB0_1231:
	s_add_u32 s34, s36, 0x200000
	s_addc_u32 s35, s37, 0
	s_add_u32 s38, s36, 0x400000
	s_addc_u32 s39, s37, 0
	s_add_u32 s36, s36, 0x600000
	s_addc_u32 s37, s37, 0
	s_mov_b64 s[0:1], -1
	s_and_b64 vcc, exec, s[30:31]
	v_lshlrev_b32_e32 v115, 4, v128
	s_cbranch_vccz .LBB0_1233
	global_load_dwordx4 v[14:17], v115, s[24:25]
	global_load_dwordx4 v[18:21], v115, s[34:35]
	global_load_dwordx4 v[22:25], v115, s[38:39]
	global_load_dwordx4 v[26:29], v115, s[36:37]
	s_mov_b64 s[0:1], 0
	global_load_dwordx4 v[200:203], v115, s[24:25] offset:1024
	global_load_dwordx4 v[200:203], v115, s[24:25] offset:2048
	global_load_dwordx4 v[200:203], v115, s[24:25] offset:3072
	global_load_dwordx4 v[200:203], v115, s[34:35] offset:1024
	global_load_dwordx4 v[200:203], v115, s[34:35] offset:2048
	global_load_dwordx4 v[200:203], v115, s[34:35] offset:3072
	global_load_dwordx4 v[200:203], v115, s[38:39] offset:1024
	global_load_dwordx4 v[200:203], v115, s[38:39] offset:2048
	global_load_dwordx4 v[200:203], v115, s[38:39] offset:3072
	global_load_dwordx4 v[200:203], v115, s[36:37] offset:1024
	global_load_dwordx4 v[200:203], v115, s[36:37] offset:2048
	global_load_dwordx4 v[200:203], v115, s[36:37] offset:3072
	s_waitcnt vmcnt(0)
	v_pk_add_f32 v[16:17], v[16:17], v[20:21]
	v_pk_add_f32 v[14:15], v[14:15], v[18:19]
	v_pk_add_f32 v[18:19], v[24:25], v[28:29]
	v_pk_add_f32 v[20:21], v[22:23], v[26:27]
	v_pk_add_f32 v[22:23], v[16:17], v[18:19]
	v_pk_add_f32 v[20:21], v[14:15], v[20:21]

; __device__ __forceinline__ void row_final2(const FinPtrs (&r)[NR], const float* g, int lane) {
;     ...
;             else { const float* gls = r[k].gls;
;                 gl = (((const f32x4*)gls)[lane + 64 * j] + ((const f32x4*)(gls + (size_t)TS * D))[lane + 64 * j]) + (((const f32x4*)(gls + (size_t)2 * TS * D))[lane + 64 * j] + ((const f32x4*)(gls + (size_t)3 * TS * D))[lane + 64 * j]); }
.LBB0_1247:
	s_add_u32 s24, s28, 0x200000
	s_addc_u32 s25, s29, 0
	s_add_u32 s30, s28, 0x400000
	s_addc_u32 s31, s29, 0
	s_add_u32 s28, s28, 0x600000
	v_cndmask_b32_e64 v0, 0, 1, s[26:27]
	s_addc_u32 s29, s29, 0
	v_cmp_ne_u32_e64 s[0:1], 1, v0
	s_andn2_b64 vcc, exec, s[26:27]
	s_mov_b64 s[26:27], -1
	s_cbranch_vccnz .LBB0_1255
	global_load_dwordx4 v[0:3], v115, s[16:17]
	global_load_dwordx4 v[118:121], v115, s[24:25]
	global_load_dwordx4 v[122:125], v115, s[30:31]
	global_load_dwordx4 v[134:137], v115, s[28:29]
	global_load_dwordx4 v[200:203], v115, s[16:17] offset:1024
	global_load_dwordx4 v[200:203], v115, s[16:17] offset:2048
	global_load_dwordx4 v[200:203], v115, s[16:17] offset:3072
	global_load_dwordx4 v[200:203], v115, s[24:25] offset:1024
	global_load_dwordx4 v[200:203], v115, s[24:25] offset:2048
	global_load_dwordx4 v[200:203], v115, s[24:25] offset:3072
	global_load_dwordx4 v[200:203], v115, s[30:31] offset:1024
	global_load_dwordx4 v[200:203], v115, s[30:31] offset:2048
	global_load_dwordx4 v[200:203], v115, s[30:31] offset:3072
	global_load_dwordx4 v[200:203], v115, s[28:29] offset:1024
	global_load_dwordx4 v[200:203], v115, s[28:29] offset:2048
	global_load_dwordx4 v[200:203], v115, s[28:29] offset:3072
	s_waitcnt vmcnt(0)
	v_pk_add_f32 v[2:3], v[2:3], v[120:121]
	v_pk_add_f32 v[0:1], v[0:1], v[118:119]
	v_pk_add_f32 v[6:7], v[124:125], v[136:137]
	v_pk_add_f32 v[10:11], v[122:123], v[134:135]
	v_pk_add_f32 v[2:3], v[2:3], v[6:7]
	v_pk_add_f32 v[0:1], v[0:1], v[10:11]
	s_cbranch_execz .LBB0_1256

; __device__ __forceinline__ void row_final2(const FinPtrs (&r)[NR], const float* g, int lane) {
;     ...
;             else { const float* gls = r[k].gls;
;                 gl = (((const f32x4*)gls)[lane + 64 * j] + ((const f32x4*)(gls + (size_t)TS * D))[lane + 64 * j]) + (((const f32x4*)(gls + (size_t)2 * TS * D))[lane + 64 * j] + ((const f32x4*)(gls + (size_t)3 * TS * D))[lane + 64 * j]); }
.LBB0_1263:
	s_add_u32 s16, s22, 0x200000
	s_addc_u32 s17, s23, 0
	s_add_u32 s24, s22, 0x400000
	s_addc_u32 s25, s23, 0
	s_add_u32 s22, s22, 0x600000
	v_cndmask_b32_e64 v36, 0, 1, s[20:21]
	s_addc_u32 s23, s23, 0
	v_cmp_ne_u32_e64 s[0:1], 1, v36
	s_andn2_b64 vcc, exec, s[20:21]
	s_mov_b64 s[20:21], -1
	s_cbranch_vccnz .LBB0_1271
	global_load_dwordx4 v[36:39], v115, s[14:15]
	global_load_dwordx4 v[118:121], v115, s[16:17]
	global_load_dwordx4 v[122:125], v115, s[24:25]
	global_load_dwordx4 v[134:137], v115, s[22:23]
	global_load_dwordx4 v[200:203], v115, s[14:15] offset:1024
	global_load_dwordx4 v[200:203], v115, s[14:15] offset:2048
	global_load_dwordx4 v[200:203], v115, s[14:15] offset:3072
	global_load_dwordx4 v[200:203], v115, s[16:17] offset:1024
	global_load_dwordx4 v[200:203], v115, s[16:17] offset:2048
	global_load_dwordx4 v[200:203], v115, s[16:17] offset:3072
	global_load_dwordx4 v[200:203], v115, s[24:25] offset:1024
	global_load_dwordx4 v[200:203], v115, s[24:25] offset:2048
	global_load_dwordx4 v[200:203], v115, s[24:25] offset:3072
	global_load_dwordx4 v[200:203], v115, s[22:23] offset:1024
	global_load_dwordx4 v[200:203], v115, s[22:23] offset:2048
	global_load_dwordx4 v[200:203], v115, s[22:23] offset:3072
	s_waitcnt vmcnt(0)
	v_pk_add_f32 v[38:39], v[38:39], v[120:121]
	v_pk_add_f32 v[36:37], v[36:37], v[118:119]
	v_pk_add_f32 v[42:43], v[124:125], v[136:137]
	v_pk_add_f32 v[46:47], v[122:123], v[134:135]
	v_pk_add_f32 v[38:39], v[38:39], v[42:43]
	v_pk_add_f32 v[36:37], v[36:37], v[46:47]
	s_cbranch_execz .LBB0_1272
